# Wout epilogue variant: v_permlane32_swap pre-swap + one ds_bpermute per dword (no select), 16 rows x 64 contiguous bytes per access
# speedup vs baseline: 1.0115x; 1.0021x over previous
;   DI void operator()(const pg8::f32x4 (&acc)[2][2][4][2], const pg8::Unit& u, int wr, int wc, int fr, int fq) const {
;     const int row0 = u.pm * 256 + wr * 64 + fr, col0 = u.pn * 256 + wc * 32 + 8 * fq;
;     const int b = (u.pm * 256) / TT;
; #pragma unroll
;     for (int ai = 0; ai < 2; ++ai)
; #pragma unroll
;       for (int m = 0; m < 4; ++m) {
;         const int row = row0 + ai * 128 + m * 16;
;         const int t = row - b * TT;
;         const bool isc = t >= TL;
;         float* dst = isc ? xc + ((size_t)b * TC + (t - TL)) * DM : xout + ((size_t)b * TL + t) * DM;
;         const float* src = src_input ? (isc ? cin + ((size_t)b * TC + (t - TL)) * DM : xin + ((size_t)b * TL + t) * DM) : dst;
;         const float* gate = modl + (size_t)(isc ? 16 : b) * 6144 + gi * DM;
; #pragma unroll
;         for (int bj = 0; bj < 2; ++bj) {
;           const int col = col0 + bj * 128;
; #pragma unroll
;           for (int n = 0; n < 2; ++n) {
;             pg8::f32x4 sv = *(const pg8::f32x4*)(src + col + 4 * n);
;             pg8::f32x4 gv = *(const pg8::f32x4*)(gate + col + 4 * n);
;             pg8::f32x4 o = sv + gv * acc[ai][bj][m][n];
;             *(pg8::f32x4*)(dst + col + 4 * n) = o;
;           }
;         }
;       }
;   }
.LBB0_1141:
	v_lshl_or_b32 v142, s30, 8, v150
	v_mov_b32_e32 v141, s34
	v_ashrrev_i32_e32 v143, 31, v142
	v_cndmask_b32_e64 v141, v141, 16, s[8:9]
	v_mov_b64_e32 v[154:155], s[20:21]
	s_movk_i32 s8, 0x6000
	v_lshlrev_b64 v[142:143], 2, v[142:143]
	v_mad_i64_i32 v[154:155], s[8:9], v141, s8, v[154:155]
	v_lshl_add_u64 v[162:163], v[146:147], 0, v[142:143]
	v_lshl_add_u64 v[164:165], v[154:155], 0, v[142:143]
	v_lshl_add_u64 v[166:167], v[144:145], 0, v[142:143]
	s_mov_b64 s[50:51], 0x10000
	s_mov_b64 s[8:9], 0x50000
	v_and_b32_e32 v158, 63, v182
	v_lshrrev_b32_e32 v159, 2, v158
	v_and_b32_e32 v160, 3, v158
	v_and_b32_e32 v161, 1, v158
	v_lshlrev_b32_e32 v161, 5, v161
	v_and_b32_e32 v168, 2, v158
	v_lshl_add_u32 v161, v168, 3, v161
	v_add_u32_e32 v161, v161, v159
	v_lshlrev_b32_e32 v218, 2, v161
	v_lshrrev_b32_e32 v161, 4, v158
	v_and_b32_e32 v168, 15, v158
	v_lshlrev_b32_e32 v169, 4, v160
	v_lshlrev_b32_e32 v161, 5, v161
	v_sub_u32_e32 v169, v169, v161
	v_sub_u32_e32 v170, v159, v168
	v_lshl_add_u32 v170, v170, 12, v169
	v_ashrrev_i32_e32 v171, 31, v170
	v_ashrrev_i32_e32 v168, 31, v169
	v_add_co_u32_e32 v220, vcc, v162, v170
	s_nop 1
	v_addc_co_u32_e32 v221, vcc, v163, v171, vcc
	v_add_co_u32_e32 v222, vcc, v166, v170
	s_nop 1
	v_addc_co_u32_e32 v223, vcc, v167, v171, vcc
	v_add_co_u32_e32 v164, vcc, v164, v169
	s_nop 1
	v_addc_co_u32_e32 v165, vcc, v165, v168, vcc
	global_load_dwordx4 v[202:205], v[164:165], off
	global_load_dwordx4 v[206:209], v[164:165], off offset:64
	global_load_dwordx4 v[210:213], v[164:165], off offset:512
	global_load_dwordx4 v[214:217], v[164:165], off offset:576
	global_load_dwordx4 v[224:227], v[220:221], off
	global_load_dwordx4 v[228:231], v[220:221], off offset:64
	global_load_dwordx4 v[232:235], v[220:221], off offset:512
	global_load_dwordx4 v[236:239], v[220:221], off offset:576
	v_lshl_add_u64 v[220:221], v[220:221], 0, s[50:51]
	global_load_dwordx4 v[240:243], v[220:221], off
	global_load_dwordx4 v[244:247], v[220:221], off offset:64
	global_load_dwordx4 v[248:251], v[220:221], off offset:512
	global_load_dwordx4 v[176:179], v[220:221], off offset:576
	v_permlane32_swap_b32_e32 v124, v120
	v_permlane32_swap_b32_e32 v125, v121
	v_permlane32_swap_b32_e32 v126, v122
	v_permlane32_swap_b32_e32 v127, v123
	ds_bpermute_b32 v140, v218, v124
	ds_bpermute_b32 v141, v218, v125
	ds_bpermute_b32 v142, v218, v126
	ds_bpermute_b32 v143, v218, v127
	ds_bpermute_b32 v144, v218, v120
	ds_bpermute_b32 v145, v218, v121
	ds_bpermute_b32 v146, v218, v122
	ds_bpermute_b32 v147, v218, v123
	s_waitcnt lgkmcnt(4)
	s_waitcnt vmcnt(4)
	v_pk_fma_f32 v[226:227], v[142:143], v[204:205], v[226:227]
	v_pk_fma_f32 v[224:225], v[140:141], v[202:203], v[224:225]
	global_store_dwordx4 v[222:223], v[224:227], off
	v_permlane32_swap_b32_e32 v116, v112
	v_permlane32_swap_b32_e32 v117, v113
	v_permlane32_swap_b32_e32 v118, v114
	v_permlane32_swap_b32_e32 v119, v115
	ds_bpermute_b32 v140, v218, v116
	ds_bpermute_b32 v141, v218, v117
	ds_bpermute_b32 v142, v218, v118
	ds_bpermute_b32 v143, v218, v119
	s_waitcnt lgkmcnt(4)
	v_pk_fma_f32 v[230:231], v[146:147], v[208:209], v[230:231]
	v_pk_fma_f32 v[228:229], v[144:145], v[206:207], v[228:229]
	global_store_dwordx4 v[222:223], v[228:231], off offset:64
	ds_bpermute_b32 v144, v218, v112
	ds_bpermute_b32 v145, v218, v113
	ds_bpermute_b32 v146, v218, v114
	ds_bpermute_b32 v147, v218, v115
	s_waitcnt lgkmcnt(4)
	v_pk_fma_f32 v[234:235], v[142:143], v[212:213], v[234:235]
	v_pk_fma_f32 v[232:233], v[140:141], v[210:211], v[232:233]
	global_store_dwordx4 v[222:223], v[232:235], off offset:512
	v_permlane32_swap_b32_e32 v108, v104
	v_permlane32_swap_b32_e32 v109, v105
	v_permlane32_swap_b32_e32 v110, v106
	v_permlane32_swap_b32_e32 v111, v107
	ds_bpermute_b32 v140, v218, v108
	ds_bpermute_b32 v141, v218, v109
	ds_bpermute_b32 v142, v218, v110
	ds_bpermute_b32 v143, v218, v111
	s_waitcnt lgkmcnt(4)
	v_pk_fma_f32 v[238:239], v[146:147], v[216:217], v[238:239]
	v_pk_fma_f32 v[236:237], v[144:145], v[214:215], v[236:237]
	global_store_dwordx4 v[222:223], v[236:239], off offset:576
	v_lshl_add_u64 v[220:221], v[220:221], 0, s[50:51]
	global_load_dwordx4 v[224:227], v[220:221], off
	global_load_dwordx4 v[228:231], v[220:221], off offset:64
	global_load_dwordx4 v[232:235], v[220:221], off offset:512
	global_load_dwordx4 v[236:239], v[220:221], off offset:576
	ds_bpermute_b32 v144, v218, v104
	ds_bpermute_b32 v145, v218, v105
	ds_bpermute_b32 v146, v218, v106
	ds_bpermute_b32 v147, v218, v107
	s_waitcnt lgkmcnt(4)
	s_waitcnt vmcnt(8)
	v_lshl_add_u64 v[222:223], v[222:223], 0, s[50:51]
	v_pk_fma_f32 v[242:243], v[142:143], v[204:205], v[242:243]
	v_pk_fma_f32 v[240:241], v[140:141], v[202:203], v[240:241]
	global_store_dwordx4 v[222:223], v[240:243], off
	v_permlane32_swap_b32_e32 v100, v96
	v_permlane32_swap_b32_e32 v101, v97
	v_permlane32_swap_b32_e32 v102, v98
	v_permlane32_swap_b32_e32 v103, v99
	ds_bpermute_b32 v140, v218, v100
	ds_bpermute_b32 v141, v218, v101
	ds_bpermute_b32 v142, v218, v102
	ds_bpermute_b32 v143, v218, v103
	s_waitcnt lgkmcnt(4)
	v_pk_fma_f32 v[246:247], v[146:147], v[208:209], v[246:247]
	v_pk_fma_f32 v[244:245], v[144:145], v[206:207], v[244:245]
	global_store_dwordx4 v[222:223], v[244:247], off offset:64
	ds_bpermute_b32 v144, v218, v96
	ds_bpermute_b32 v145, v218, v97
	ds_bpermute_b32 v146, v218, v98
	ds_bpermute_b32 v147, v218, v99
	s_waitcnt lgkmcnt(4)
;   DI void operator()(const pg8::f32x4 (&acc)[2][2][4][2], const pg8::Unit& u, int wr, int wc, int fr, int fq) const {
;     const int row0 = u.pm * 256 + wr * 64 + fr, col0 = u.pn * 256 + wc * 32 + 8 * fq;
;     const int b = (u.pm * 256) / TT;
; #pragma unroll
;     for (int ai = 0; ai < 2; ++ai)
; #pragma unroll
;       for (int m = 0; m < 4; ++m) {
;         const int row = row0 + ai * 128 + m * 16;
;         const int t = row - b * TT;
;         const bool isc = t >= TL;
;         float* dst = isc ? xc + ((size_t)b * TC + (t - TL)) * DM : xout + ((size_t)b * TL + t) * DM;
;         const float* src = src_input ? (isc ? cin + ((size_t)b * TC + (t - TL)) * DM : xin + ((size_t)b * TL + t) * DM) : dst;
;         const float* gate = modl + (size_t)(isc ? 16 : b) * 6144 + gi * DM;
; #pragma unroll
;         for (int bj = 0; bj < 2; ++bj) {
;           const int col = col0 + bj * 128;
; #pragma unroll
;           for (int n = 0; n < 2; ++n) {
;             pg8::f32x4 sv = *(const pg8::f32x4*)(src + col + 4 * n);
;             pg8::f32x4 gv = *(const pg8::f32x4*)(gate + col + 4 * n);
;             pg8::f32x4 o = sv + gv * acc[ai][bj][m][n];
;             *(pg8::f32x4*)(dst + col + 4 * n) = o;
;           }
;         }
;       }
;   }
	v_pk_fma_f32 v[250:251], v[142:143], v[212:213], v[250:251]
	v_pk_fma_f32 v[248:249], v[140:141], v[210:211], v[248:249]
	global_store_dwordx4 v[222:223], v[248:251], off offset:512
	v_permlane32_swap_b32_e32 v92, v88
	v_permlane32_swap_b32_e32 v93, v89
	v_permlane32_swap_b32_e32 v94, v90
	v_permlane32_swap_b32_e32 v95, v91
	ds_bpermute_b32 v140, v218, v92
	ds_bpermute_b32 v141, v218, v93
	ds_bpermute_b32 v142, v218, v94
	ds_bpermute_b32 v143, v218, v95
	s_waitcnt lgkmcnt(4)
	v_pk_fma_f32 v[178:179], v[146:147], v[216:217], v[178:179]
	v_pk_fma_f32 v[176:177], v[144:145], v[214:215], v[176:177]
	global_store_dwordx4 v[222:223], v[176:179], off offset:576
	v_lshl_add_u64 v[220:221], v[220:221], 0, s[50:51]
	global_load_dwordx4 v[240:243], v[220:221], off
	global_load_dwordx4 v[244:247], v[220:221], off offset:64
	global_load_dwordx4 v[248:251], v[220:221], off offset:512
	global_load_dwordx4 v[176:179], v[220:221], off offset:576
	ds_bpermute_b32 v144, v218, v88
	ds_bpermute_b32 v145, v218, v89
	ds_bpermute_b32 v146, v218, v90
	ds_bpermute_b32 v147, v218, v91
	s_waitcnt lgkmcnt(4)
	s_waitcnt vmcnt(8)
	v_lshl_add_u64 v[222:223], v[222:223], 0, s[50:51]
	v_pk_fma_f32 v[226:227], v[142:143], v[204:205], v[226:227]
	v_pk_fma_f32 v[224:225], v[140:141], v[202:203], v[224:225]
	global_store_dwordx4 v[222:223], v[224:227], off
	v_permlane32_swap_b32_e32 v84, v80
	v_permlane32_swap_b32_e32 v85, v81
	v_permlane32_swap_b32_e32 v86, v82
	v_permlane32_swap_b32_e32 v87, v83
	ds_bpermute_b32 v140, v218, v84
	ds_bpermute_b32 v141, v218, v85
	ds_bpermute_b32 v142, v218, v86
	ds_bpermute_b32 v143, v218, v87
	s_waitcnt lgkmcnt(4)
	v_pk_fma_f32 v[230:231], v[146:147], v[208:209], v[230:231]
	v_pk_fma_f32 v[228:229], v[144:145], v[206:207], v[228:229]
	global_store_dwordx4 v[222:223], v[228:231], off offset:64
	ds_bpermute_b32 v144, v218, v80
	ds_bpermute_b32 v145, v218, v81
	ds_bpermute_b32 v146, v218, v82
	ds_bpermute_b32 v147, v218, v83
	s_waitcnt lgkmcnt(4)
	v_pk_fma_f32 v[234:235], v[142:143], v[212:213], v[234:235]
	v_pk_fma_f32 v[232:233], v[140:141], v[210:211], v[232:233]
	global_store_dwordx4 v[222:223], v[232:235], off offset:512
	v_permlane32_swap_b32_e32 v76, v72
	v_permlane32_swap_b32_e32 v77, v73
	v_permlane32_swap_b32_e32 v78, v74
	v_permlane32_swap_b32_e32 v79, v75
	ds_bpermute_b32 v140, v218, v76
	ds_bpermute_b32 v141, v218, v77
	ds_bpermute_b32 v142, v218, v78
	ds_bpermute_b32 v143, v218, v79
	s_waitcnt lgkmcnt(4)
	v_pk_fma_f32 v[238:239], v[146:147], v[216:217], v[238:239]
	v_pk_fma_f32 v[236:237], v[144:145], v[214:215], v[236:237]
	global_store_dwordx4 v[222:223], v[236:239], off offset:576
	v_lshl_add_u64 v[220:221], v[220:221], 0, s[8:9]
	global_load_dwordx4 v[224:227], v[220:221], off
	global_load_dwordx4 v[228:231], v[220:221], off offset:64
	global_load_dwordx4 v[232:235], v[220:221], off offset:512
	global_load_dwordx4 v[236:239], v[220:221], off offset:576
	ds_bpermute_b32 v144, v218, v72
	ds_bpermute_b32 v145, v218, v73
	ds_bpermute_b32 v146, v218, v74
	ds_bpermute_b32 v147, v218, v75
	s_waitcnt lgkmcnt(4)
	s_waitcnt vmcnt(8)
	v_lshl_add_u64 v[222:223], v[222:223], 0, s[50:51]
	v_pk_fma_f32 v[242:243], v[142:143], v[204:205], v[242:243]
	v_pk_fma_f32 v[240:241], v[140:141], v[202:203], v[240:241]
	global_store_dwordx4 v[222:223], v[240:243], off
	v_permlane32_swap_b32_e32 v68, v64
	v_permlane32_swap_b32_e32 v69, v65
	v_permlane32_swap_b32_e32 v70, v66
	v_permlane32_swap_b32_e32 v71, v67
	ds_bpermute_b32 v140, v218, v68
	ds_bpermute_b32 v141, v218, v69
	ds_bpermute_b32 v142, v218, v70
	ds_bpermute_b32 v143, v218, v71
	s_waitcnt lgkmcnt(4)
	v_pk_fma_f32 v[246:247], v[146:147], v[208:209], v[246:247]
	v_pk_fma_f32 v[244:245], v[144:145], v[206:207], v[244:245]
	global_store_dwordx4 v[222:223], v[244:247], off offset:64
	ds_bpermute_b32 v144, v218, v64
	ds_bpermute_b32 v145, v218, v65
	ds_bpermute_b32 v146, v218, v66
	ds_bpermute_b32 v147, v218, v67
	s_waitcnt lgkmcnt(4)
	v_pk_fma_f32 v[250:251], v[142:143], v[212:213], v[250:251]
	v_pk_fma_f32 v[248:249], v[140:141], v[210:211], v[248:249]
	global_store_dwordx4 v[222:223], v[248:251], off offset:512
	v_permlane32_swap_b32_e32 v60, v56
	v_permlane32_swap_b32_e32 v61, v57
	v_permlane32_swap_b32_e32 v62, v58
	v_permlane32_swap_b32_e32 v63, v59
	ds_bpermute_b32 v140, v218, v60
	ds_bpermute_b32 v141, v218, v61
	ds_bpermute_b32 v142, v218, v62
	ds_bpermute_b32 v143, v218, v63
	s_waitcnt lgkmcnt(4)
	v_pk_fma_f32 v[178:179], v[146:147], v[216:217], v[178:179]
	v_pk_fma_f32 v[176:177], v[144:145], v[214:215], v[176:177]
	global_store_dwordx4 v[222:223], v[176:179], off offset:576
	v_lshl_add_u64 v[220:221], v[220:221], 0, s[50:51]
	global_load_dwordx4 v[240:243], v[220:221], off
	global_load_dwordx4 v[244:247], v[220:221], off offset:64
	global_load_dwordx4 v[248:251], v[220:221], off offset:512
	global_load_dwordx4 v[176:179], v[220:221], off offset:576
	ds_bpermute_b32 v144, v218, v56
	ds_bpermute_b32 v145, v218, v57
	ds_bpermute_b32 v146, v218, v58
	ds_bpermute_b32 v147, v218, v59
	s_waitcnt lgkmcnt(4)
	s_waitcnt vmcnt(8)
	v_lshl_add_u64 v[222:223], v[222:223], 0, s[8:9]
	v_pk_fma_f32 v[226:227], v[142:143], v[204:205], v[226:227]
	v_pk_fma_f32 v[224:225], v[140:141], v[202:203], v[224:225]
	global_store_dwordx4 v[222:223], v[224:227], off
	v_permlane32_swap_b32_e32 v52, v48
	v_permlane32_swap_b32_e32 v53, v49
	v_permlane32_swap_b32_e32 v54, v50
	v_permlane32_swap_b32_e32 v55, v51
	ds_bpermute_b32 v140, v218, v52
	ds_bpermute_b32 v141, v218, v53
	ds_bpermute_b32 v142, v218, v54
	ds_bpermute_b32 v143, v218, v55
	s_waitcnt lgkmcnt(4)
;   DI void operator()(const pg8::f32x4 (&acc)[2][2][4][2], const pg8::Unit& u, int wr, int wc, int fr, int fq) const {
;     const int row0 = u.pm * 256 + wr * 64 + fr, col0 = u.pn * 256 + wc * 32 + 8 * fq;
;     const int b = (u.pm * 256) / TT;
; #pragma unroll
;     for (int ai = 0; ai < 2; ++ai)
; #pragma unroll
;       for (int m = 0; m < 4; ++m) {
;         const int row = row0 + ai * 128 + m * 16;
;         const int t = row - b * TT;
;         const bool isc = t >= TL;
;         float* dst = isc ? xc + ((size_t)b * TC + (t - TL)) * DM : xout + ((size_t)b * TL + t) * DM;
;         const float* src = src_input ? (isc ? cin + ((size_t)b * TC + (t - TL)) * DM : xin + ((size_t)b * TL + t) * DM) : dst;
;         const float* gate = modl + (size_t)(isc ? 16 : b) * 6144 + gi * DM;
; #pragma unroll
;         for (int bj = 0; bj < 2; ++bj) {
;           const int col = col0 + bj * 128;
; #pragma unroll
;           for (int n = 0; n < 2; ++n) {
;             pg8::f32x4 sv = *(const pg8::f32x4*)(src + col + 4 * n);
;             pg8::f32x4 gv = *(const pg8::f32x4*)(gate + col + 4 * n);
;             pg8::f32x4 o = sv + gv * acc[ai][bj][m][n];
;             *(pg8::f32x4*)(dst + col + 4 * n) = o;
;           }
;         }
;       }
;   }
	v_pk_fma_f32 v[230:231], v[146:147], v[208:209], v[230:231]
	v_pk_fma_f32 v[228:229], v[144:145], v[206:207], v[228:229]
	global_store_dwordx4 v[222:223], v[228:231], off offset:64
	ds_bpermute_b32 v144, v218, v48
	ds_bpermute_b32 v145, v218, v49
	ds_bpermute_b32 v146, v218, v50
	ds_bpermute_b32 v147, v218, v51
	s_waitcnt lgkmcnt(4)
	v_pk_fma_f32 v[234:235], v[142:143], v[212:213], v[234:235]
	v_pk_fma_f32 v[232:233], v[140:141], v[210:211], v[232:233]
	global_store_dwordx4 v[222:223], v[232:235], off offset:512
	v_permlane32_swap_b32_e32 v44, v40
	v_permlane32_swap_b32_e32 v45, v41
	v_permlane32_swap_b32_e32 v46, v42
	v_permlane32_swap_b32_e32 v47, v43
	ds_bpermute_b32 v140, v218, v44
	ds_bpermute_b32 v141, v218, v45
	ds_bpermute_b32 v142, v218, v46
	ds_bpermute_b32 v143, v218, v47
	s_waitcnt lgkmcnt(4)
	v_pk_fma_f32 v[238:239], v[146:147], v[216:217], v[238:239]
	v_pk_fma_f32 v[236:237], v[144:145], v[214:215], v[236:237]
	global_store_dwordx4 v[222:223], v[236:239], off offset:576
	v_lshl_add_u64 v[220:221], v[220:221], 0, s[50:51]
	global_load_dwordx4 v[224:227], v[220:221], off
	global_load_dwordx4 v[228:231], v[220:221], off offset:64
	global_load_dwordx4 v[232:235], v[220:221], off offset:512
	global_load_dwordx4 v[236:239], v[220:221], off offset:576
	ds_bpermute_b32 v144, v218, v40
	ds_bpermute_b32 v145, v218, v41
	ds_bpermute_b32 v146, v218, v42
	ds_bpermute_b32 v147, v218, v43
	s_waitcnt lgkmcnt(4)
	s_waitcnt vmcnt(8)
	v_lshl_add_u64 v[222:223], v[222:223], 0, s[50:51]
	v_pk_fma_f32 v[242:243], v[142:143], v[204:205], v[242:243]
	v_pk_fma_f32 v[240:241], v[140:141], v[202:203], v[240:241]
	global_store_dwordx4 v[222:223], v[240:243], off
	v_permlane32_swap_b32_e32 v36, v32
	v_permlane32_swap_b32_e32 v37, v33
	v_permlane32_swap_b32_e32 v38, v34
	v_permlane32_swap_b32_e32 v39, v35
	ds_bpermute_b32 v140, v218, v36
	ds_bpermute_b32 v141, v218, v37
	ds_bpermute_b32 v142, v218, v38
	ds_bpermute_b32 v143, v218, v39
	s_waitcnt lgkmcnt(4)
	v_pk_fma_f32 v[246:247], v[146:147], v[208:209], v[246:247]
	v_pk_fma_f32 v[244:245], v[144:145], v[206:207], v[244:245]
	global_store_dwordx4 v[222:223], v[244:247], off offset:64
	ds_bpermute_b32 v144, v218, v32
	ds_bpermute_b32 v145, v218, v33
	ds_bpermute_b32 v146, v218, v34
	ds_bpermute_b32 v147, v218, v35
	s_waitcnt lgkmcnt(4)
	v_pk_fma_f32 v[250:251], v[142:143], v[212:213], v[250:251]
	v_pk_fma_f32 v[248:249], v[140:141], v[210:211], v[248:249]
	global_store_dwordx4 v[222:223], v[248:251], off offset:512
	v_permlane32_swap_b32_e32 v28, v24
	v_permlane32_swap_b32_e32 v29, v25
	v_permlane32_swap_b32_e32 v30, v26
	v_permlane32_swap_b32_e32 v31, v27
	ds_bpermute_b32 v140, v218, v28
	ds_bpermute_b32 v141, v218, v29
	ds_bpermute_b32 v142, v218, v30
	ds_bpermute_b32 v143, v218, v31
	s_waitcnt lgkmcnt(4)
	v_pk_fma_f32 v[178:179], v[146:147], v[216:217], v[178:179]
	v_pk_fma_f32 v[176:177], v[144:145], v[214:215], v[176:177]
	global_store_dwordx4 v[222:223], v[176:179], off offset:576
	v_lshl_add_u64 v[220:221], v[220:221], 0, s[50:51]
	global_load_dwordx4 v[240:243], v[220:221], off
	global_load_dwordx4 v[244:247], v[220:221], off offset:64
	global_load_dwordx4 v[248:251], v[220:221], off offset:512
	global_load_dwordx4 v[176:179], v[220:221], off offset:576
	ds_bpermute_b32 v144, v218, v24
	ds_bpermute_b32 v145, v218, v25
	ds_bpermute_b32 v146, v218, v26
	ds_bpermute_b32 v147, v218, v27
	s_waitcnt lgkmcnt(4)
	s_waitcnt vmcnt(8)
	v_lshl_add_u64 v[222:223], v[222:223], 0, s[50:51]
	v_pk_fma_f32 v[226:227], v[142:143], v[204:205], v[226:227]
	v_pk_fma_f32 v[224:225], v[140:141], v[202:203], v[224:225]
	global_store_dwordx4 v[222:223], v[224:227], off
	v_permlane32_swap_b32_e32 v20, v16
	v_permlane32_swap_b32_e32 v21, v17
	v_permlane32_swap_b32_e32 v22, v18
	v_permlane32_swap_b32_e32 v23, v19
	ds_bpermute_b32 v140, v218, v20
	ds_bpermute_b32 v141, v218, v21
	ds_bpermute_b32 v142, v218, v22
	ds_bpermute_b32 v143, v218, v23
	s_waitcnt lgkmcnt(4)
	v_pk_fma_f32 v[230:231], v[146:147], v[208:209], v[230:231]
	v_pk_fma_f32 v[228:229], v[144:145], v[206:207], v[228:229]
	global_store_dwordx4 v[222:223], v[228:231], off offset:64
	ds_bpermute_b32 v144, v218, v16
	ds_bpermute_b32 v145, v218, v17
	ds_bpermute_b32 v146, v218, v18
	ds_bpermute_b32 v147, v218, v19
	s_waitcnt lgkmcnt(4)
	v_pk_fma_f32 v[234:235], v[142:143], v[212:213], v[234:235]
	v_pk_fma_f32 v[232:233], v[140:141], v[210:211], v[232:233]
	global_store_dwordx4 v[222:223], v[232:235], off offset:512
	v_permlane32_swap_b32_e32 v12, v8
	v_permlane32_swap_b32_e32 v13, v9
	v_permlane32_swap_b32_e32 v14, v10
	v_permlane32_swap_b32_e32 v15, v11
	ds_bpermute_b32 v140, v218, v12
	ds_bpermute_b32 v141, v218, v13
	ds_bpermute_b32 v142, v218, v14
	ds_bpermute_b32 v143, v218, v15
	s_waitcnt lgkmcnt(4)
	v_pk_fma_f32 v[238:239], v[146:147], v[216:217], v[238:239]
	v_pk_fma_f32 v[236:237], v[144:145], v[214:215], v[236:237]
	global_store_dwordx4 v[222:223], v[236:239], off offset:576
	ds_bpermute_b32 v144, v218, v8
	ds_bpermute_b32 v145, v218, v9
	ds_bpermute_b32 v146, v218, v10
	ds_bpermute_b32 v147, v218, v11
	s_waitcnt lgkmcnt(4)
	s_waitcnt vmcnt(4)
	v_lshl_add_u64 v[222:223], v[222:223], 0, s[50:51]
	v_pk_fma_f32 v[242:243], v[142:143], v[204:205], v[242:243]
	v_pk_fma_f32 v[240:241], v[140:141], v[202:203], v[240:241]
	global_store_dwordx4 v[222:223], v[240:243], off
	v_permlane32_swap_b32_e32 v4, v0
	v_permlane32_swap_b32_e32 v5, v1
	v_permlane32_swap_b32_e32 v6, v2
	v_permlane32_swap_b32_e32 v7, v3
	ds_bpermute_b32 v140, v218, v4
	ds_bpermute_b32 v141, v218, v5
	ds_bpermute_b32 v142, v218, v6
	ds_bpermute_b32 v143, v218, v7
	s_waitcnt lgkmcnt(4)
	v_pk_fma_f32 v[246:247], v[146:147], v[208:209], v[246:247]
	v_pk_fma_f32 v[244:245], v[144:145], v[206:207], v[244:245]
	global_store_dwordx4 v[222:223], v[244:247], off offset:64
	ds_bpermute_b32 v144, v218, v0
	ds_bpermute_b32 v145, v218, v1
	ds_bpermute_b32 v146, v218, v2
	ds_bpermute_b32 v147, v218, v3
	s_waitcnt lgkmcnt(4)
	v_pk_fma_f32 v[250:251], v[142:143], v[212:213], v[250:251]
	v_pk_fma_f32 v[248:249], v[140:141], v[210:211], v[248:249]
	global_store_dwordx4 v[222:223], v[248:251], off offset:512
	s_waitcnt lgkmcnt(0)
	v_pk_fma_f32 v[178:179], v[146:147], v[216:217], v[178:179]
	v_pk_fma_f32 v[176:177], v[144:145], v[214:215], v[176:177]
	global_store_dwordx4 v[222:223], v[176:179], off offset:576
	s_mov_b64 s[4:5], -1
	s_andn2_b64 vcc, exec, s[2:3]
	s_cbranch_vccnz .LBB0_1128
	s_andn2_b64 vcc, exec, s[16:17]
	s_cbranch_vccnz .LBB0_1127
	s_barrier
	s_branch .LBB0_1127
